# hand-written fast epilogues for plain/q-scale/sigmoid tiles of the main GEMM (fewer instructions per tile); branch-merge epilogue as before
# speedup vs baseline: 1.0071x; 1.0071x over previous
.LBB0_372:
	s_add_u32 s8, s6, 0xfff80080
	s_addc_u32 s9, s7, -1
	s_add_i32 s21, 0, 0x10000
	v_add_u32_e32 v143, s21, v167
	ds_read_b128 v[148:151], v143
	ds_read_b128 v[152:155], v143 offset:1024
	ds_read_b128 v[156:159], v143 offset:2048
	ds_read_b128 v[160:163], v143 offset:3072
	s_cmp_eq_u32 s20, 28
	s_cselect_b32 s11, s17, s9
	s_cselect_b32 s10, s16, s8
	s_cselect_b32 s9, s19, s15
	s_cselect_b32 s8, s18, s13
	v_lshl_add_u64 v[164:165], s[6:7], 0, v[138:139]
	s_add_i32 m0, s40, 0xc000
	ds_read_b128 v[172:175], v171
	ds_read_b128 v[180:183], v171 offset:1024
	ds_read_b128 v[184:187], v171 offset:2048
	ds_read_b128 v[188:191], v171 offset:3072
	ds_read_b128 v[192:195], v171 offset:4096
	ds_read_b128 v[196:199], v171 offset:5120
	ds_read_b128 v[200:203], v171 offset:6144
	ds_read_b128 v[204:207], v171 offset:7168
	global_load_lds_dwordx4 v[164:165], off
	v_lshl_add_u64 v[164:165], s[6:7], 0, v[140:141]
	s_add_i32 m0, s40, 0xe000
	s_nop 0
	global_load_lds_dwordx4 v[164:165], off
	s_waitcnt lgkmcnt(8)
	s_barrier
	s_waitcnt lgkmcnt(0)
	s_setprio 1
	s_waitcnt lgkmcnt(0)
	v_mfma_f32_16x16x32_bf16 v[126:129], v[148:151], v[172:175], v[126:129]
	v_mfma_f32_16x16x32_bf16 v[122:125], v[156:159], v[172:175], v[122:125]
	v_mfma_f32_16x16x32_bf16 v[110:113], v[148:151], v[184:187], v[110:113]
	v_mfma_f32_16x16x32_bf16 v[106:109], v[156:159], v[184:187], v[106:109]
	v_mfma_f32_16x16x32_bf16 v[94:97], v[148:151], v[192:195], v[94:97]
	v_mfma_f32_16x16x32_bf16 v[90:93], v[156:159], v[192:195], v[90:93]
	v_mfma_f32_16x16x32_bf16 v[78:81], v[148:151], v[200:203], v[78:81]
	v_mfma_f32_16x16x32_bf16 v[74:77], v[156:159], v[200:203], v[74:77]
	v_mfma_f32_16x16x32_bf16 v[126:129], v[152:155], v[180:183], v[126:129]
	v_mfma_f32_16x16x32_bf16 v[122:125], v[160:163], v[180:183], v[122:125]
	v_mfma_f32_16x16x32_bf16 v[110:113], v[152:155], v[188:191], v[110:113]
	v_mfma_f32_16x16x32_bf16 v[106:109], v[160:163], v[188:191], v[106:109]
	v_mfma_f32_16x16x32_bf16 v[94:97], v[152:155], v[196:199], v[94:97]
	v_mfma_f32_16x16x32_bf16 v[90:93], v[160:163], v[196:199], v[90:93]
	v_mfma_f32_16x16x32_bf16 v[78:81], v[152:155], v[204:207], v[78:81]
	v_mfma_f32_16x16x32_bf16 v[74:77], v[160:163], v[204:207], v[74:77]
	s_setprio 0
	s_barrier
	s_add_i32 s24, 0, 0x14000
	s_add_i32 s21, s21, s39
	v_add_u32_e32 v143, s24, v167
	v_lshl_add_u64 v[164:165], s[8:9], 0, v[134:135]
	s_mov_b32 m0, s21
	ds_read_b128 v[208:211], v143
	ds_read_b128 v[212:215], v143 offset:1024
	ds_read_b128 v[216:219], v143 offset:2048
	ds_read_b128 v[220:223], v143 offset:3072
	global_load_lds_dwordx4 v[164:165], off
	v_lshl_add_u64 v[176:177], s[8:9], 0, v[130:131]
	s_add_i32 m0, s21, 0x2000
	s_nop 0
	global_load_lds_dwordx4 v[176:177], off
	s_barrier
	s_waitcnt lgkmcnt(0)
	s_setprio 1
	s_waitcnt lgkmcnt(0)
	v_mfma_f32_16x16x32_bf16 v[118:121], v[208:211], v[172:175], v[118:121]
	v_mfma_f32_16x16x32_bf16 v[114:117], v[216:219], v[172:175], v[114:117]
	v_mfma_f32_16x16x32_bf16 v[102:105], v[208:211], v[184:187], v[102:105]
	v_mfma_f32_16x16x32_bf16 v[98:101], v[216:219], v[184:187], v[98:101]
	v_mfma_f32_16x16x32_bf16 v[86:89], v[208:211], v[192:195], v[86:89]
	v_mfma_f32_16x16x32_bf16 v[82:85], v[216:219], v[192:195], v[82:85]
	v_mfma_f32_16x16x32_bf16 v[70:73], v[208:211], v[200:203], v[70:73]
	v_mfma_f32_16x16x32_bf16 v[66:69], v[216:219], v[200:203], v[66:69]
	v_mfma_f32_16x16x32_bf16 v[118:121], v[212:215], v[180:183], v[118:121]
	v_mfma_f32_16x16x32_bf16 v[114:117], v[220:223], v[180:183], v[114:117]
	v_mfma_f32_16x16x32_bf16 v[102:105], v[212:215], v[188:191], v[102:105]
	v_mfma_f32_16x16x32_bf16 v[98:101], v[220:223], v[188:191], v[98:101]
	v_mfma_f32_16x16x32_bf16 v[86:89], v[212:215], v[196:199], v[86:89]
	v_mfma_f32_16x16x32_bf16 v[82:85], v[220:223], v[196:199], v[82:85]
	v_mfma_f32_16x16x32_bf16 v[70:73], v[212:215], v[204:207], v[70:73]
	v_mfma_f32_16x16x32_bf16 v[66:69], v[220:223], v[204:207], v[66:69]
	s_setprio 0
	s_mov_b32 m0, s40
	v_lshl_add_u64 v[224:225], s[10:11], 0, v[136:137]
	s_barrier
	ds_read_b128 v[172:175], v171 offset:16384
	ds_read_b128 v[180:183], v171 offset:17408
	ds_read_b128 v[184:187], v171 offset:18432
	ds_read_b128 v[188:191], v171 offset:19456
	ds_read_b128 v[192:195], v171 offset:20480
	ds_read_b128 v[196:199], v171 offset:21504
	ds_read_b128 v[200:203], v171 offset:22528
	ds_read_b128 v[204:207], v171 offset:23552
	global_load_lds_dwordx4 v[224:225], off
	v_lshl_add_u64 v[236:237], s[10:11], 0, v[132:133]
	s_mov_b32 m0, s41
	s_nop 0
	global_load_lds_dwordx4 v[236:237], off
	s_barrier
	s_waitcnt lgkmcnt(0)
	s_setprio 1
	s_waitcnt lgkmcnt(0)
	v_mfma_f32_16x16x32_bf16 v[62:65], v[148:151], v[172:175], v[62:65]
	v_mfma_f32_16x16x32_bf16 v[58:61], v[156:159], v[172:175], v[58:61]
	v_mfma_f32_16x16x32_bf16 v[46:49], v[148:151], v[184:187], v[46:49]
	v_mfma_f32_16x16x32_bf16 v[42:45], v[156:159], v[184:187], v[42:45]
	v_mfma_f32_16x16x32_bf16 v[28:31], v[148:151], v[192:195], v[28:31]
	v_mfma_f32_16x16x32_bf16 v[24:27], v[156:159], v[192:195], v[24:27]
	v_mfma_f32_16x16x32_bf16 v[12:15], v[148:151], v[200:203], v[12:15]
	v_mfma_f32_16x16x32_bf16 v[8:11], v[156:159], v[200:203], v[8:11]
	v_mfma_f32_16x16x32_bf16 v[62:65], v[152:155], v[180:183], v[62:65]
	v_mfma_f32_16x16x32_bf16 v[58:61], v[160:163], v[180:183], v[58:61]
	v_mfma_f32_16x16x32_bf16 v[46:49], v[152:155], v[188:191], v[46:49]
	v_mfma_f32_16x16x32_bf16 v[42:45], v[160:163], v[188:191], v[42:45]
	v_mfma_f32_16x16x32_bf16 v[28:31], v[152:155], v[196:199], v[28:31]
	v_mfma_f32_16x16x32_bf16 v[24:27], v[160:163], v[196:199], v[24:27]
	v_mfma_f32_16x16x32_bf16 v[12:15], v[152:155], v[204:207], v[12:15]
	v_mfma_f32_16x16x32_bf16 v[8:11], v[160:163], v[204:207], v[8:11]
	s_setprio 0
	s_barrier
	s_add_u32 s22, s8, 0x80000
	s_addc_u32 s23, s9, 0
	s_add_i32 s21, s24, s39
	v_lshl_add_u64 v[148:149], s[22:23], 0, v[134:135]
	s_mov_b32 m0, s21
	s_nop 0
	global_load_lds_dwordx4 v[148:149], off
	v_lshl_add_u64 v[148:149], s[22:23], 0, v[130:131]
	s_add_i32 m0, s21, 0x2000
	s_nop 0
	global_load_lds_dwordx4 v[148:149], off
	s_waitcnt vmcnt(6)
	s_barrier
	s_setprio 1
	v_mfma_f32_16x16x32_bf16 v[54:57], v[208:211], v[172:175], v[54:57]
	v_mfma_f32_16x16x32_bf16 v[50:53], v[216:219], v[172:175], v[50:53]
	v_mfma_f32_16x16x32_bf16 v[38:41], v[208:211], v[184:187], v[38:41]
	v_mfma_f32_16x16x32_bf16 v[34:37], v[216:219], v[184:187], v[34:37]
	v_mfma_f32_16x16x32_bf16 v[20:23], v[208:211], v[192:195], v[20:23]
	v_mfma_f32_16x16x32_bf16 v[16:19], v[216:219], v[192:195], v[16:19]
	v_mfma_f32_16x16x32_bf16 v[4:7], v[208:211], v[200:203], v[4:7]
	v_mfma_f32_16x16x32_bf16 v[0:3], v[216:219], v[200:203], v[0:3]
	v_mfma_f32_16x16x32_bf16 v[54:57], v[212:215], v[180:183], v[54:57]
	v_mfma_f32_16x16x32_bf16 v[50:53], v[220:223], v[180:183], v[50:53]
	v_mfma_f32_16x16x32_bf16 v[38:41], v[212:215], v[188:191], v[38:41]
	v_mfma_f32_16x16x32_bf16 v[34:37], v[220:223], v[188:191], v[34:37]
	v_mfma_f32_16x16x32_bf16 v[20:23], v[212:215], v[196:199], v[20:23]
	v_mfma_f32_16x16x32_bf16 v[16:19], v[220:223], v[196:199], v[16:19]
	v_mfma_f32_16x16x32_bf16 v[4:7], v[212:215], v[204:207], v[4:7]
	v_mfma_f32_16x16x32_bf16 v[0:3], v[220:223], v[204:207], v[0:3]
	s_setprio 0
	s_add_i32 s21, 0, 0x18000
	v_add_u32_e32 v143, s21, v167
	s_barrier
	ds_read_b128 v[148:151], v143
	ds_read_b128 v[152:155], v143 offset:1024
	ds_read_b128 v[156:159], v143 offset:2048
	ds_read_b128 v[160:163], v143 offset:3072
	s_add_u32 s10, s10, 0x80000
	s_addc_u32 s11, s11, 0
	s_mov_b32 m0, s42
	v_lshl_add_u64 v[208:209], s[10:11], 0, v[136:137]
	ds_read_b128 v[172:175], v171 offset:32768
	ds_read_b128 v[180:183], v171 offset:33792
	ds_read_b128 v[184:187], v171 offset:34816
	ds_read_b128 v[188:191], v171 offset:35840
	ds_read_b128 v[192:195], v171 offset:36864
	ds_read_b128 v[196:199], v171 offset:37888
	ds_read_b128 v[200:203], v171 offset:38912
	ds_read_b128 v[204:207], v171 offset:39936
	global_load_lds_dwordx4 v[208:209], off
	v_lshl_add_u64 v[208:209], s[10:11], 0, v[132:133]
	s_mov_b32 m0, s43
	s_nop 0
	global_load_lds_dwordx4 v[208:209], off
	s_waitcnt lgkmcnt(8)
	s_barrier
	s_waitcnt lgkmcnt(0)
	s_setprio 1
	s_waitcnt lgkmcnt(0)
	v_mfma_f32_16x16x32_bf16 v[126:129], v[148:151], v[172:175], v[126:129]
	v_mfma_f32_16x16x32_bf16 v[122:125], v[156:159], v[172:175], v[122:125]
	v_mfma_f32_16x16x32_bf16 v[110:113], v[148:151], v[184:187], v[110:113]
	v_mfma_f32_16x16x32_bf16 v[106:109], v[156:159], v[184:187], v[106:109]
	v_mfma_f32_16x16x32_bf16 v[94:97], v[148:151], v[192:195], v[94:97]
	v_mfma_f32_16x16x32_bf16 v[90:93], v[156:159], v[192:195], v[90:93]
	v_mfma_f32_16x16x32_bf16 v[78:81], v[148:151], v[200:203], v[78:81]
	v_mfma_f32_16x16x32_bf16 v[74:77], v[156:159], v[200:203], v[74:77]
	v_mfma_f32_16x16x32_bf16 v[126:129], v[152:155], v[180:183], v[126:129]
	v_mfma_f32_16x16x32_bf16 v[122:125], v[160:163], v[180:183], v[122:125]
	v_mfma_f32_16x16x32_bf16 v[110:113], v[152:155], v[188:191], v[110:113]
	v_mfma_f32_16x16x32_bf16 v[106:109], v[160:163], v[188:191], v[106:109]
	v_mfma_f32_16x16x32_bf16 v[94:97], v[152:155], v[196:199], v[94:97]
	v_mfma_f32_16x16x32_bf16 v[90:93], v[160:163], v[196:199], v[90:93]
	v_mfma_f32_16x16x32_bf16 v[78:81], v[152:155], v[204:207], v[78:81]
	v_mfma_f32_16x16x32_bf16 v[74:77], v[160:163], v[204:207], v[74:77]
	s_setprio 0
	s_barrier
	s_add_i32 s10, 0, 0x1c000
	s_add_i32 s11, s21, s39
	v_add_u32_e32 v143, s10, v167
	v_lshl_add_u64 v[164:165], v[164:165], 0, s[88:89]
	s_mov_b32 m0, s11
	ds_read_b128 v[208:211], v143
	ds_read_b128 v[212:215], v143 offset:1024
	ds_read_b128 v[216:219], v143 offset:2048
	ds_read_b128 v[220:223], v143 offset:3072
	global_load_lds_dwordx4 v[164:165], off
	v_lshl_add_u64 v[164:165], v[176:177], 0, s[88:89]
	s_add_i32 m0, s11, 0x2000
	s_nop 0
	global_load_lds_dwordx4 v[164:165], off
	s_barrier
	s_waitcnt lgkmcnt(0)
	s_setprio 1
	s_waitcnt lgkmcnt(0)
	v_mfma_f32_16x16x32_bf16 v[118:121], v[208:211], v[172:175], v[118:121]
	v_mfma_f32_16x16x32_bf16 v[114:117], v[216:219], v[172:175], v[114:117]
	v_mfma_f32_16x16x32_bf16 v[102:105], v[208:211], v[184:187], v[102:105]
	v_mfma_f32_16x16x32_bf16 v[98:101], v[216:219], v[184:187], v[98:101]
	v_mfma_f32_16x16x32_bf16 v[86:89], v[208:211], v[192:195], v[86:89]
	v_mfma_f32_16x16x32_bf16 v[82:85], v[216:219], v[192:195], v[82:85]
	v_mfma_f32_16x16x32_bf16 v[70:73], v[208:211], v[200:203], v[70:73]
	v_mfma_f32_16x16x32_bf16 v[66:69], v[216:219], v[200:203], v[66:69]
	v_mfma_f32_16x16x32_bf16 v[118:121], v[212:215], v[180:183], v[118:121]
	v_mfma_f32_16x16x32_bf16 v[114:117], v[220:223], v[180:183], v[114:117]
	v_mfma_f32_16x16x32_bf16 v[102:105], v[212:215], v[188:191], v[102:105]
	v_mfma_f32_16x16x32_bf16 v[98:101], v[220:223], v[188:191], v[98:101]
	v_mfma_f32_16x16x32_bf16 v[86:89], v[212:215], v[196:199], v[86:89]
	v_mfma_f32_16x16x32_bf16 v[82:85], v[220:223], v[196:199], v[82:85]
	v_mfma_f32_16x16x32_bf16 v[70:73], v[212:215], v[204:207], v[70:73]
	v_mfma_f32_16x16x32_bf16 v[66:69], v[220:223], v[204:207], v[66:69]
	s_setprio 0
	s_mov_b32 m0, s46
	v_lshl_add_u64 v[164:165], v[224:225], 0, s[88:89]
	s_barrier
	ds_read_b128 v[172:175], v171 offset:49152
	ds_read_b128 v[180:183], v171 offset:50176
	ds_read_b128 v[184:187], v171 offset:51200
	ds_read_b128 v[188:191], v171 offset:52224
	ds_read_b128 v[192:195], v171 offset:53248
	ds_read_b128 v[196:199], v171 offset:54272
	ds_read_b128 v[200:203], v171 offset:55296
	ds_read_b128 v[204:207], v171 offset:56320
	global_load_lds_dwordx4 v[164:165], off
	v_lshl_add_u64 v[164:165], v[236:237], 0, s[88:89]
	s_mov_b32 m0, s47
	s_nop 0
	global_load_lds_dwordx4 v[164:165], off
	s_barrier
	s_waitcnt lgkmcnt(0)
	s_setprio 1
	s_waitcnt lgkmcnt(0)
	v_mfma_f32_16x16x32_bf16 v[62:65], v[148:151], v[172:175], v[62:65]
	v_mfma_f32_16x16x32_bf16 v[58:61], v[156:159], v[172:175], v[58:61]
	v_mfma_f32_16x16x32_bf16 v[46:49], v[148:151], v[184:187], v[46:49]
	v_mfma_f32_16x16x32_bf16 v[42:45], v[156:159], v[184:187], v[42:45]
	v_mfma_f32_16x16x32_bf16 v[28:31], v[148:151], v[192:195], v[28:31]
	v_mfma_f32_16x16x32_bf16 v[24:27], v[156:159], v[192:195], v[24:27]
	v_mfma_f32_16x16x32_bf16 v[12:15], v[148:151], v[200:203], v[12:15]
	v_mfma_f32_16x16x32_bf16 v[8:11], v[156:159], v[200:203], v[8:11]
	v_mfma_f32_16x16x32_bf16 v[62:65], v[152:155], v[180:183], v[62:65]
	v_mfma_f32_16x16x32_bf16 v[58:61], v[160:163], v[180:183], v[58:61]
	v_mfma_f32_16x16x32_bf16 v[46:49], v[152:155], v[188:191], v[46:49]
	v_mfma_f32_16x16x32_bf16 v[42:45], v[160:163], v[188:191], v[42:45]
	v_mfma_f32_16x16x32_bf16 v[28:31], v[152:155], v[196:199], v[28:31]
	v_mfma_f32_16x16x32_bf16 v[24:27], v[160:163], v[196:199], v[24:27]
	v_mfma_f32_16x16x32_bf16 v[12:15], v[152:155], v[204:207], v[12:15]
	v_mfma_f32_16x16x32_bf16 v[8:11], v[160:163], v[204:207], v[8:11]
	s_setprio 0
	s_barrier
	s_add_u32 s8, s8, 0x80080
	s_addc_u32 s9, s9, 0
	s_add_i32 s10, s10, s39
	v_lshl_add_u64 v[148:149], s[8:9], 0, v[134:135]
	s_mov_b32 m0, s10
	s_nop 0
	global_load_lds_dwordx4 v[148:149], off
	v_lshl_add_u64 v[148:149], s[8:9], 0, v[130:131]
	s_add_i32 m0, s10, 0x2000
	s_nop 0
	global_load_lds_dwordx4 v[148:149], off
	s_waitcnt vmcnt(6)
	s_barrier
	s_setprio 1
	v_mfma_f32_16x16x32_bf16 v[54:57], v[208:211], v[172:175], v[54:57]
	v_mfma_f32_16x16x32_bf16 v[50:53], v[216:219], v[172:175], v[50:53]
	v_mfma_f32_16x16x32_bf16 v[38:41], v[208:211], v[184:187], v[38:41]
	v_mfma_f32_16x16x32_bf16 v[34:37], v[216:219], v[184:187], v[34:37]
	v_mfma_f32_16x16x32_bf16 v[20:23], v[208:211], v[192:195], v[20:23]
	v_mfma_f32_16x16x32_bf16 v[16:19], v[216:219], v[192:195], v[16:19]
	v_mfma_f32_16x16x32_bf16 v[4:7], v[208:211], v[200:203], v[4:7]
	v_mfma_f32_16x16x32_bf16 v[0:3], v[216:219], v[200:203], v[0:3]
	v_mfma_f32_16x16x32_bf16 v[54:57], v[212:215], v[180:183], v[54:57]
	v_mfma_f32_16x16x32_bf16 v[50:53], v[220:223], v[180:183], v[50:53]
	v_mfma_f32_16x16x32_bf16 v[38:41], v[212:215], v[188:191], v[38:41]
	v_mfma_f32_16x16x32_bf16 v[34:37], v[220:223], v[188:191], v[34:37]
	v_mfma_f32_16x16x32_bf16 v[20:23], v[212:215], v[196:199], v[20:23]
	v_mfma_f32_16x16x32_bf16 v[16:19], v[220:223], v[196:199], v[16:19]
	v_mfma_f32_16x16x32_bf16 v[4:7], v[212:215], v[204:207], v[4:7]
	v_mfma_f32_16x16x32_bf16 v[0:3], v[220:223], v[204:207], v[0:3]
	s_setprio 0
	s_add_i32 s20, s20, 2
	s_add_u32 s6, s6, 0x100
	s_addc_u32 s7, s7, 0
	s_add_u32 s13, s13, 0x100
	s_addc_u32 s15, s15, 0
	s_cmp_gt_u32 s20, 29
	s_barrier
	s_cbranch_scc0 .LBB0_372
	s_sub_i32 s6, s51, 8
	s_cmp_lt_u32 s6, 8
	s_cbranch_scc1 .Lmain_old
	s_sub_i32 s6, s51, 32
	s_cmp_lt_u32 s6, 12
	s_cbranch_scc1 .Lmain_old
	v_add_u32_e32 v216, s45, v166
	s_cmp_ge_u32 s51, 0x44
	s_cbranch_scc1 .Lmain_sig
	s_sub_i32 s6, s51, 44
	s_mov_b32 s7, 0x25e51000
	s_mov_b32 s13, 0x15e51000
	s_cmp_lt_i32 s6, 0
	s_cselect_b32 s6, s51, s6
	s_cselect_b32 s7, s13, s7
	s_lshr_b32 s13, s6, 3
	s_lshl_b32 s13, s13, 26
	s_add_i32 s7, s7, s13
	s_and_b32 s6, s6, 7
	s_lshl_b32 s6, s6, 9
	s_add_i32 s7, s7, s6
	s_lshl_b32 s6, s31, 20
	s_add_i32 s7, s7, s6
	s_add_u32 s22, s76, s7
	s_addc_u32 s23, s77, 0
	v_lshl_add_u32 v216, v216, 12, v32
	s_lshr_b32 s6, s51, 3
	s_cmp_eq_u32 s6, 3
	s_cbranch_scc1 .Lmain_q
	s_add_u32 s10, s22, 0
	s_addc_u32 s11, s23, 0
	v_cvt_pk_bf16_f32 v148, v126, v127
	v_cvt_pk_bf16_f32 v149, v128, v129
	v_cvt_pk_bf16_f32 v150, v122, v123
	v_cvt_pk_bf16_f32 v151, v124, v125
	global_store_dwordx4 v216, v[148:151], s[10:11] nt
	v_cvt_pk_bf16_f32 v152, v118, v119
	v_cvt_pk_bf16_f32 v153, v120, v121
	v_cvt_pk_bf16_f32 v154, v114, v115
	v_cvt_pk_bf16_f32 v155, v116, v117
	global_store_dwordx4 v216, v[152:155], s[10:11] offset:256 nt
	s_add_u32 s10, s22, 0x10000
	s_addc_u32 s11, s23, 0
	v_cvt_pk_bf16_f32 v156, v110, v111
	v_cvt_pk_bf16_f32 v157, v112, v113
	v_cvt_pk_bf16_f32 v158, v106, v107
	v_cvt_pk_bf16_f32 v159, v108, v109
	global_store_dwordx4 v216, v[156:159], s[10:11] nt
	v_cvt_pk_bf16_f32 v160, v102, v103
	v_cvt_pk_bf16_f32 v161, v104, v105
	v_cvt_pk_bf16_f32 v162, v98, v99
	v_cvt_pk_bf16_f32 v163, v100, v101
	global_store_dwordx4 v216, v[160:163], s[10:11] offset:256 nt
	s_add_u32 s10, s22, 0x20000
	s_addc_u32 s11, s23, 0
	v_cvt_pk_bf16_f32 v148, v94, v95
	v_cvt_pk_bf16_f32 v149, v96, v97
	v_cvt_pk_bf16_f32 v150, v90, v91
	v_cvt_pk_bf16_f32 v151, v92, v93
	global_store_dwordx4 v216, v[148:151], s[10:11] nt
	v_cvt_pk_bf16_f32 v152, v86, v87
	v_cvt_pk_bf16_f32 v153, v88, v89
	v_cvt_pk_bf16_f32 v154, v82, v83
	v_cvt_pk_bf16_f32 v155, v84, v85
	global_store_dwordx4 v216, v[152:155], s[10:11] offset:256 nt
	s_add_u32 s10, s22, 0x30000
	s_addc_u32 s11, s23, 0
	v_cvt_pk_bf16_f32 v156, v78, v79
	v_cvt_pk_bf16_f32 v157, v80, v81
	v_cvt_pk_bf16_f32 v158, v74, v75
	v_cvt_pk_bf16_f32 v159, v76, v77
	global_store_dwordx4 v216, v[156:159], s[10:11] nt
	v_cvt_pk_bf16_f32 v160, v70, v71
	v_cvt_pk_bf16_f32 v161, v72, v73
	v_cvt_pk_bf16_f32 v162, v66, v67
	v_cvt_pk_bf16_f32 v163, v68, v69
	global_store_dwordx4 v216, v[160:163], s[10:11] offset:256 nt
	s_add_u32 s10, s22, 0x80000
	s_addc_u32 s11, s23, 0
	v_cvt_pk_bf16_f32 v148, v62, v63
	v_cvt_pk_bf16_f32 v149, v64, v65
	v_cvt_pk_bf16_f32 v150, v58, v59
	v_cvt_pk_bf16_f32 v151, v60, v61
	global_store_dwordx4 v216, v[148:151], s[10:11] nt
	v_cvt_pk_bf16_f32 v152, v54, v55
	v_cvt_pk_bf16_f32 v153, v56, v57
	v_cvt_pk_bf16_f32 v154, v50, v51
	v_cvt_pk_bf16_f32 v155, v52, v53
	global_store_dwordx4 v216, v[152:155], s[10:11] offset:256 nt
	s_add_u32 s10, s22, 0x90000
	s_addc_u32 s11, s23, 0
	v_cvt_pk_bf16_f32 v156, v46, v47
	v_cvt_pk_bf16_f32 v157, v48, v49
	v_cvt_pk_bf16_f32 v158, v42, v43
	v_cvt_pk_bf16_f32 v159, v44, v45
	global_store_dwordx4 v216, v[156:159], s[10:11] nt
	v_cvt_pk_bf16_f32 v160, v38, v39
	v_cvt_pk_bf16_f32 v161, v40, v41
	v_cvt_pk_bf16_f32 v162, v34, v35
	v_cvt_pk_bf16_f32 v163, v36, v37
	global_store_dwordx4 v216, v[160:163], s[10:11] offset:256 nt
	s_add_u32 s10, s22, 0xa0000
	s_addc_u32 s11, s23, 0
	v_cvt_pk_bf16_f32 v148, v28, v29
	v_cvt_pk_bf16_f32 v149, v30, v31
	v_cvt_pk_bf16_f32 v150, v24, v25
	v_cvt_pk_bf16_f32 v151, v26, v27
	global_store_dwordx4 v216, v[148:151], s[10:11] nt
	v_cvt_pk_bf16_f32 v152, v20, v21
	v_cvt_pk_bf16_f32 v153, v22, v23
	v_cvt_pk_bf16_f32 v154, v16, v17
	v_cvt_pk_bf16_f32 v155, v18, v19
	global_store_dwordx4 v216, v[152:155], s[10:11] offset:256 nt
	s_add_u32 s10, s22, 0xb0000
	s_addc_u32 s11, s23, 0
	v_cvt_pk_bf16_f32 v156, v12, v13
	v_cvt_pk_bf16_f32 v157, v14, v15
	v_cvt_pk_bf16_f32 v158, v8, v9
	v_cvt_pk_bf16_f32 v159, v10, v11
	global_store_dwordx4 v216, v[156:159], s[10:11] nt
	v_cvt_pk_bf16_f32 v160, v4, v5
	v_cvt_pk_bf16_f32 v161, v6, v7
	v_cvt_pk_bf16_f32 v162, v0, v1
	v_cvt_pk_bf16_f32 v163, v2, v3
	global_store_dwordx4 v216, v[160:163], s[10:11] offset:256 nt
	s_branch .LBB0_364
.Lmain_q:
	s_mov_b32 s6, 0x3e0293ee
	s_add_u32 s10, s22, 0
	s_addc_u32 s11, s23, 0
	v_pk_mul_f32 v[126:127], v[126:127], s[6:7] op_sel_hi:[1,0]
	v_pk_mul_f32 v[128:129], v[128:129], s[6:7] op_sel_hi:[1,0]
	v_pk_mul_f32 v[122:123], v[122:123], s[6:7] op_sel_hi:[1,0]
	v_pk_mul_f32 v[124:125], v[124:125], s[6:7] op_sel_hi:[1,0]
	v_cvt_pk_bf16_f32 v148, v126, v127
	v_cvt_pk_bf16_f32 v149, v128, v129
	v_cvt_pk_bf16_f32 v150, v122, v123
	v_cvt_pk_bf16_f32 v151, v124, v125
	global_store_dwordx4 v216, v[148:151], s[10:11] nt
	v_pk_mul_f32 v[118:119], v[118:119], s[6:7] op_sel_hi:[1,0]
	v_pk_mul_f32 v[120:121], v[120:121], s[6:7] op_sel_hi:[1,0]
	v_pk_mul_f32 v[114:115], v[114:115], s[6:7] op_sel_hi:[1,0]
	v_pk_mul_f32 v[116:117], v[116:117], s[6:7] op_sel_hi:[1,0]
	v_cvt_pk_bf16_f32 v152, v118, v119
	v_cvt_pk_bf16_f32 v153, v120, v121
	v_cvt_pk_bf16_f32 v154, v114, v115
	v_cvt_pk_bf16_f32 v155, v116, v117
	global_store_dwordx4 v216, v[152:155], s[10:11] offset:256 nt
	s_add_u32 s10, s22, 0x10000
	s_addc_u32 s11, s23, 0
	v_pk_mul_f32 v[110:111], v[110:111], s[6:7] op_sel_hi:[1,0]
	v_pk_mul_f32 v[112:113], v[112:113], s[6:7] op_sel_hi:[1,0]
	v_pk_mul_f32 v[106:107], v[106:107], s[6:7] op_sel_hi:[1,0]
	v_pk_mul_f32 v[108:109], v[108:109], s[6:7] op_sel_hi:[1,0]
	v_cvt_pk_bf16_f32 v156, v110, v111
	v_cvt_pk_bf16_f32 v157, v112, v113
	v_cvt_pk_bf16_f32 v158, v106, v107
	v_cvt_pk_bf16_f32 v159, v108, v109
	global_store_dwordx4 v216, v[156:159], s[10:11] nt
	v_pk_mul_f32 v[102:103], v[102:103], s[6:7] op_sel_hi:[1,0]
	v_pk_mul_f32 v[104:105], v[104:105], s[6:7] op_sel_hi:[1,0]
	v_pk_mul_f32 v[98:99], v[98:99], s[6:7] op_sel_hi:[1,0]
	v_pk_mul_f32 v[100:101], v[100:101], s[6:7] op_sel_hi:[1,0]
	v_cvt_pk_bf16_f32 v160, v102, v103
	v_cvt_pk_bf16_f32 v161, v104, v105
	v_cvt_pk_bf16_f32 v162, v98, v99
	v_cvt_pk_bf16_f32 v163, v100, v101
	global_store_dwordx4 v216, v[160:163], s[10:11] offset:256 nt
	s_add_u32 s10, s22, 0x20000
	s_addc_u32 s11, s23, 0
	v_pk_mul_f32 v[94:95], v[94:95], s[6:7] op_sel_hi:[1,0]
	v_pk_mul_f32 v[96:97], v[96:97], s[6:7] op_sel_hi:[1,0]
	v_pk_mul_f32 v[90:91], v[90:91], s[6:7] op_sel_hi:[1,0]
	v_pk_mul_f32 v[92:93], v[92:93], s[6:7] op_sel_hi:[1,0]
	v_cvt_pk_bf16_f32 v148, v94, v95
	v_cvt_pk_bf16_f32 v149, v96, v97
	v_cvt_pk_bf16_f32 v150, v90, v91
	v_cvt_pk_bf16_f32 v151, v92, v93
	global_store_dwordx4 v216, v[148:151], s[10:11] nt
	v_pk_mul_f32 v[86:87], v[86:87], s[6:7] op_sel_hi:[1,0]
	v_pk_mul_f32 v[88:89], v[88:89], s[6:7] op_sel_hi:[1,0]
	v_pk_mul_f32 v[82:83], v[82:83], s[6:7] op_sel_hi:[1,0]
	v_pk_mul_f32 v[84:85], v[84:85], s[6:7] op_sel_hi:[1,0]
	v_cvt_pk_bf16_f32 v152, v86, v87
	v_cvt_pk_bf16_f32 v153, v88, v89
	v_cvt_pk_bf16_f32 v154, v82, v83
	v_cvt_pk_bf16_f32 v155, v84, v85
	global_store_dwordx4 v216, v[152:155], s[10:11] offset:256 nt
	s_add_u32 s10, s22, 0x30000
	s_addc_u32 s11, s23, 0
	v_pk_mul_f32 v[78:79], v[78:79], s[6:7] op_sel_hi:[1,0]
	v_pk_mul_f32 v[80:81], v[80:81], s[6:7] op_sel_hi:[1,0]
	v_pk_mul_f32 v[74:75], v[74:75], s[6:7] op_sel_hi:[1,0]
	v_pk_mul_f32 v[76:77], v[76:77], s[6:7] op_sel_hi:[1,0]
	v_cvt_pk_bf16_f32 v156, v78, v79
	v_cvt_pk_bf16_f32 v157, v80, v81
	v_cvt_pk_bf16_f32 v158, v74, v75
	v_cvt_pk_bf16_f32 v159, v76, v77
	global_store_dwordx4 v216, v[156:159], s[10:11] nt
	v_pk_mul_f32 v[70:71], v[70:71], s[6:7] op_sel_hi:[1,0]
	v_pk_mul_f32 v[72:73], v[72:73], s[6:7] op_sel_hi:[1,0]
	v_pk_mul_f32 v[66:67], v[66:67], s[6:7] op_sel_hi:[1,0]
	v_pk_mul_f32 v[68:69], v[68:69], s[6:7] op_sel_hi:[1,0]
	v_cvt_pk_bf16_f32 v160, v70, v71
	v_cvt_pk_bf16_f32 v161, v72, v73
	v_cvt_pk_bf16_f32 v162, v66, v67
	v_cvt_pk_bf16_f32 v163, v68, v69
	global_store_dwordx4 v216, v[160:163], s[10:11] offset:256 nt
	s_add_u32 s10, s22, 0x80000
	s_addc_u32 s11, s23, 0
	v_pk_mul_f32 v[62:63], v[62:63], s[6:7] op_sel_hi:[1,0]
	v_pk_mul_f32 v[64:65], v[64:65], s[6:7] op_sel_hi:[1,0]
	v_pk_mul_f32 v[58:59], v[58:59], s[6:7] op_sel_hi:[1,0]
	v_pk_mul_f32 v[60:61], v[60:61], s[6:7] op_sel_hi:[1,0]
	v_cvt_pk_bf16_f32 v148, v62, v63
	v_cvt_pk_bf16_f32 v149, v64, v65
	v_cvt_pk_bf16_f32 v150, v58, v59
	v_cvt_pk_bf16_f32 v151, v60, v61
	global_store_dwordx4 v216, v[148:151], s[10:11] nt
	v_pk_mul_f32 v[54:55], v[54:55], s[6:7] op_sel_hi:[1,0]
	v_pk_mul_f32 v[56:57], v[56:57], s[6:7] op_sel_hi:[1,0]
	v_pk_mul_f32 v[50:51], v[50:51], s[6:7] op_sel_hi:[1,0]
	v_pk_mul_f32 v[52:53], v[52:53], s[6:7] op_sel_hi:[1,0]
	v_cvt_pk_bf16_f32 v152, v54, v55
	v_cvt_pk_bf16_f32 v153, v56, v57
	v_cvt_pk_bf16_f32 v154, v50, v51
	v_cvt_pk_bf16_f32 v155, v52, v53
	global_store_dwordx4 v216, v[152:155], s[10:11] offset:256 nt
	s_add_u32 s10, s22, 0x90000
	s_addc_u32 s11, s23, 0
	v_pk_mul_f32 v[46:47], v[46:47], s[6:7] op_sel_hi:[1,0]
	v_pk_mul_f32 v[48:49], v[48:49], s[6:7] op_sel_hi:[1,0]
	v_pk_mul_f32 v[42:43], v[42:43], s[6:7] op_sel_hi:[1,0]
	v_pk_mul_f32 v[44:45], v[44:45], s[6:7] op_sel_hi:[1,0]
	v_cvt_pk_bf16_f32 v156, v46, v47
	v_cvt_pk_bf16_f32 v157, v48, v49
	v_cvt_pk_bf16_f32 v158, v42, v43
	v_cvt_pk_bf16_f32 v159, v44, v45
	global_store_dwordx4 v216, v[156:159], s[10:11] nt
	v_pk_mul_f32 v[38:39], v[38:39], s[6:7] op_sel_hi:[1,0]
	v_pk_mul_f32 v[40:41], v[40:41], s[6:7] op_sel_hi:[1,0]
	v_pk_mul_f32 v[34:35], v[34:35], s[6:7] op_sel_hi:[1,0]
	v_pk_mul_f32 v[36:37], v[36:37], s[6:7] op_sel_hi:[1,0]
	v_cvt_pk_bf16_f32 v160, v38, v39
	v_cvt_pk_bf16_f32 v161, v40, v41
	v_cvt_pk_bf16_f32 v162, v34, v35
	v_cvt_pk_bf16_f32 v163, v36, v37
	global_store_dwordx4 v216, v[160:163], s[10:11] offset:256 nt
	s_add_u32 s10, s22, 0xa0000
	s_addc_u32 s11, s23, 0
	v_pk_mul_f32 v[28:29], v[28:29], s[6:7] op_sel_hi:[1,0]
	v_pk_mul_f32 v[30:31], v[30:31], s[6:7] op_sel_hi:[1,0]
	v_pk_mul_f32 v[24:25], v[24:25], s[6:7] op_sel_hi:[1,0]
	v_pk_mul_f32 v[26:27], v[26:27], s[6:7] op_sel_hi:[1,0]
	v_cvt_pk_bf16_f32 v148, v28, v29
	v_cvt_pk_bf16_f32 v149, v30, v31
	v_cvt_pk_bf16_f32 v150, v24, v25
	v_cvt_pk_bf16_f32 v151, v26, v27
	global_store_dwordx4 v216, v[148:151], s[10:11] nt
	v_pk_mul_f32 v[20:21], v[20:21], s[6:7] op_sel_hi:[1,0]
	v_pk_mul_f32 v[22:23], v[22:23], s[6:7] op_sel_hi:[1,0]
	v_pk_mul_f32 v[16:17], v[16:17], s[6:7] op_sel_hi:[1,0]
	v_pk_mul_f32 v[18:19], v[18:19], s[6:7] op_sel_hi:[1,0]
	v_cvt_pk_bf16_f32 v152, v20, v21
	v_cvt_pk_bf16_f32 v153, v22, v23
	v_cvt_pk_bf16_f32 v154, v16, v17
	v_cvt_pk_bf16_f32 v155, v18, v19
	global_store_dwordx4 v216, v[152:155], s[10:11] offset:256 nt
	s_add_u32 s10, s22, 0xb0000
	s_addc_u32 s11, s23, 0
	v_pk_mul_f32 v[12:13], v[12:13], s[6:7] op_sel_hi:[1,0]
	v_pk_mul_f32 v[14:15], v[14:15], s[6:7] op_sel_hi:[1,0]
	v_pk_mul_f32 v[8:9], v[8:9], s[6:7] op_sel_hi:[1,0]
	v_pk_mul_f32 v[10:11], v[10:11], s[6:7] op_sel_hi:[1,0]
	v_cvt_pk_bf16_f32 v156, v12, v13
	v_cvt_pk_bf16_f32 v157, v14, v15
	v_cvt_pk_bf16_f32 v158, v8, v9
	v_cvt_pk_bf16_f32 v159, v10, v11
	global_store_dwordx4 v216, v[156:159], s[10:11] nt
	v_pk_mul_f32 v[4:5], v[4:5], s[6:7] op_sel_hi:[1,0]
	v_pk_mul_f32 v[6:7], v[6:7], s[6:7] op_sel_hi:[1,0]
	v_pk_mul_f32 v[0:1], v[0:1], s[6:7] op_sel_hi:[1,0]
	v_pk_mul_f32 v[2:3], v[2:3], s[6:7] op_sel_hi:[1,0]
	v_cvt_pk_bf16_f32 v160, v4, v5
	v_cvt_pk_bf16_f32 v161, v6, v7
	v_cvt_pk_bf16_f32 v162, v0, v1
	v_cvt_pk_bf16_f32 v163, v2, v3
	global_store_dwordx4 v216, v[160:163], s[10:11] offset:256 nt
	s_branch .LBB0_364
.Lmain_sig:
	s_mul_i32 s7, s31, 0x300000
	s_sub_i32 s6, s51, 0x44
	s_lshl_b32 s6, s6, 9
	s_add_i32 s7, s7, s6
	s_add_i32 s7, s7, 0x37f51000
	s_add_u32 s22, s76, s7
	s_addc_u32 s23, s77, 0
	v_mul_u32_u24_e32 v216, 0x3000, v216
	v_add_u32_e32 v216, v216, v32
	s_add_u32 s10, s22, 0
	s_addc_u32 s11, s23, 0
	v_mul_f32_e32 v208, 0xbfb8aa3b, v126
	v_mul_f32_e32 v209, 0xbfb8aa3b, v127
	v_mul_f32_e32 v210, 0xbfb8aa3b, v128
	v_mul_f32_e32 v211, 0xbfb8aa3b, v129
	v_mul_f32_e32 v212, 0xbfb8aa3b, v122
	v_mul_f32_e32 v213, 0xbfb8aa3b, v123
	v_mul_f32_e32 v214, 0xbfb8aa3b, v124
	v_mul_f32_e32 v215, 0xbfb8aa3b, v125
	v_exp_f32_e32 v208, v208
	v_exp_f32_e32 v209, v209
	v_exp_f32_e32 v210, v210
	v_exp_f32_e32 v211, v211
	v_exp_f32_e32 v212, v212
	v_exp_f32_e32 v213, v213
	v_exp_f32_e32 v214, v214
	v_exp_f32_e32 v215, v215
	v_add_f32_e32 v208, 1.0, v208
	v_add_f32_e32 v209, 1.0, v209
	v_add_f32_e32 v210, 1.0, v210
	v_add_f32_e32 v211, 1.0, v211
	v_add_f32_e32 v212, 1.0, v212
	v_add_f32_e32 v213, 1.0, v213
	v_add_f32_e32 v214, 1.0, v214
	v_add_f32_e32 v215, 1.0, v215
	v_rcp_f32_e32 v208, v208
	v_rcp_f32_e32 v209, v209
	v_rcp_f32_e32 v210, v210
	v_rcp_f32_e32 v211, v211
	v_rcp_f32_e32 v212, v212
	v_rcp_f32_e32 v213, v213
	v_rcp_f32_e32 v214, v214
	v_rcp_f32_e32 v215, v215
	v_cvt_pk_bf16_f32 v148, v208, v209
	v_cvt_pk_bf16_f32 v149, v210, v211
	v_cvt_pk_bf16_f32 v150, v212, v213
	v_cvt_pk_bf16_f32 v151, v214, v215
	global_store_dwordx4 v216, v[148:151], s[10:11] nt
	v_mul_f32_e32 v208, 0xbfb8aa3b, v118
	v_mul_f32_e32 v209, 0xbfb8aa3b, v119
	v_mul_f32_e32 v210, 0xbfb8aa3b, v120
	v_mul_f32_e32 v211, 0xbfb8aa3b, v121
	v_mul_f32_e32 v212, 0xbfb8aa3b, v114
	v_mul_f32_e32 v213, 0xbfb8aa3b, v115
	v_mul_f32_e32 v214, 0xbfb8aa3b, v116
	v_mul_f32_e32 v215, 0xbfb8aa3b, v117
	v_exp_f32_e32 v208, v208
	v_exp_f32_e32 v209, v209
	v_exp_f32_e32 v210, v210
	v_exp_f32_e32 v211, v211
	v_exp_f32_e32 v212, v212
	v_exp_f32_e32 v213, v213
	v_exp_f32_e32 v214, v214
	v_exp_f32_e32 v215, v215
	v_add_f32_e32 v208, 1.0, v208
	v_add_f32_e32 v209, 1.0, v209
	v_add_f32_e32 v210, 1.0, v210
	v_add_f32_e32 v211, 1.0, v211
	v_add_f32_e32 v212, 1.0, v212
	v_add_f32_e32 v213, 1.0, v213
	v_add_f32_e32 v214, 1.0, v214
	v_add_f32_e32 v215, 1.0, v215
	v_rcp_f32_e32 v208, v208
	v_rcp_f32_e32 v209, v209
	v_rcp_f32_e32 v210, v210
	v_rcp_f32_e32 v211, v211
	v_rcp_f32_e32 v212, v212
	v_rcp_f32_e32 v213, v213
	v_rcp_f32_e32 v214, v214
	v_rcp_f32_e32 v215, v215
	v_cvt_pk_bf16_f32 v152, v208, v209
	v_cvt_pk_bf16_f32 v153, v210, v211
	v_cvt_pk_bf16_f32 v154, v212, v213
	v_cvt_pk_bf16_f32 v155, v214, v215
	global_store_dwordx4 v216, v[152:155], s[10:11] offset:256 nt
	s_add_u32 s10, s22, 0x30000
	s_addc_u32 s11, s23, 0
	v_mul_f32_e32 v208, 0xbfb8aa3b, v110
	v_mul_f32_e32 v209, 0xbfb8aa3b, v111
	v_mul_f32_e32 v210, 0xbfb8aa3b, v112
	v_mul_f32_e32 v211, 0xbfb8aa3b, v113
	v_mul_f32_e32 v212, 0xbfb8aa3b, v106
	v_mul_f32_e32 v213, 0xbfb8aa3b, v107
	v_mul_f32_e32 v214, 0xbfb8aa3b, v108
	v_mul_f32_e32 v215, 0xbfb8aa3b, v109
	v_exp_f32_e32 v208, v208
	v_exp_f32_e32 v209, v209
	v_exp_f32_e32 v210, v210
	v_exp_f32_e32 v211, v211
	v_exp_f32_e32 v212, v212
	v_exp_f32_e32 v213, v213
	v_exp_f32_e32 v214, v214
	v_exp_f32_e32 v215, v215
	v_add_f32_e32 v208, 1.0, v208
	v_add_f32_e32 v209, 1.0, v209
	v_add_f32_e32 v210, 1.0, v210
	v_add_f32_e32 v211, 1.0, v211
	v_add_f32_e32 v212, 1.0, v212
	v_add_f32_e32 v213, 1.0, v213
	v_add_f32_e32 v214, 1.0, v214
	v_add_f32_e32 v215, 1.0, v215
	v_rcp_f32_e32 v208, v208
	v_rcp_f32_e32 v209, v209
	v_rcp_f32_e32 v210, v210
	v_rcp_f32_e32 v211, v211
	v_rcp_f32_e32 v212, v212
	v_rcp_f32_e32 v213, v213
	v_rcp_f32_e32 v214, v214
	v_rcp_f32_e32 v215, v215
	v_cvt_pk_bf16_f32 v156, v208, v209
	v_cvt_pk_bf16_f32 v157, v210, v211
	v_cvt_pk_bf16_f32 v158, v212, v213
	v_cvt_pk_bf16_f32 v159, v214, v215
	global_store_dwordx4 v216, v[156:159], s[10:11] nt
	v_mul_f32_e32 v208, 0xbfb8aa3b, v102
	v_mul_f32_e32 v209, 0xbfb8aa3b, v103
	v_mul_f32_e32 v210, 0xbfb8aa3b, v104
	v_mul_f32_e32 v211, 0xbfb8aa3b, v105
	v_mul_f32_e32 v212, 0xbfb8aa3b, v98
	v_mul_f32_e32 v213, 0xbfb8aa3b, v99
	v_mul_f32_e32 v214, 0xbfb8aa3b, v100
	v_mul_f32_e32 v215, 0xbfb8aa3b, v101
	v_exp_f32_e32 v208, v208
	v_exp_f32_e32 v209, v209
	v_exp_f32_e32 v210, v210
	v_exp_f32_e32 v211, v211
	v_exp_f32_e32 v212, v212
	v_exp_f32_e32 v213, v213
	v_exp_f32_e32 v214, v214
	v_exp_f32_e32 v215, v215
	v_add_f32_e32 v208, 1.0, v208
	v_add_f32_e32 v209, 1.0, v209
	v_add_f32_e32 v210, 1.0, v210
	v_add_f32_e32 v211, 1.0, v211
	v_add_f32_e32 v212, 1.0, v212
	v_add_f32_e32 v213, 1.0, v213
	v_add_f32_e32 v214, 1.0, v214
	v_add_f32_e32 v215, 1.0, v215
	v_rcp_f32_e32 v208, v208
	v_rcp_f32_e32 v209, v209
	v_rcp_f32_e32 v210, v210
	v_rcp_f32_e32 v211, v211
	v_rcp_f32_e32 v212, v212
	v_rcp_f32_e32 v213, v213
	v_rcp_f32_e32 v214, v214
	v_rcp_f32_e32 v215, v215
	v_cvt_pk_bf16_f32 v160, v208, v209
	v_cvt_pk_bf16_f32 v161, v210, v211
	v_cvt_pk_bf16_f32 v162, v212, v213
	v_cvt_pk_bf16_f32 v163, v214, v215
	global_store_dwordx4 v216, v[160:163], s[10:11] offset:256 nt
	s_add_u32 s10, s22, 0x60000
	s_addc_u32 s11, s23, 0
	v_mul_f32_e32 v208, 0xbfb8aa3b, v94
	v_mul_f32_e32 v209, 0xbfb8aa3b, v95
	v_mul_f32_e32 v210, 0xbfb8aa3b, v96
	v_mul_f32_e32 v211, 0xbfb8aa3b, v97
	v_mul_f32_e32 v212, 0xbfb8aa3b, v90
	v_mul_f32_e32 v213, 0xbfb8aa3b, v91
	v_mul_f32_e32 v214, 0xbfb8aa3b, v92
	v_mul_f32_e32 v215, 0xbfb8aa3b, v93
	v_exp_f32_e32 v208, v208
	v_exp_f32_e32 v209, v209
	v_exp_f32_e32 v210, v210
	v_exp_f32_e32 v211, v211
	v_exp_f32_e32 v212, v212
	v_exp_f32_e32 v213, v213
	v_exp_f32_e32 v214, v214
	v_exp_f32_e32 v215, v215
	v_add_f32_e32 v208, 1.0, v208
	v_add_f32_e32 v209, 1.0, v209
	v_add_f32_e32 v210, 1.0, v210
	v_add_f32_e32 v211, 1.0, v211
	v_add_f32_e32 v212, 1.0, v212
	v_add_f32_e32 v213, 1.0, v213
	v_add_f32_e32 v214, 1.0, v214
	v_add_f32_e32 v215, 1.0, v215
	v_rcp_f32_e32 v208, v208
	v_rcp_f32_e32 v209, v209
	v_rcp_f32_e32 v210, v210
	v_rcp_f32_e32 v211, v211
	v_rcp_f32_e32 v212, v212
	v_rcp_f32_e32 v213, v213
	v_rcp_f32_e32 v214, v214
	v_rcp_f32_e32 v215, v215
	v_cvt_pk_bf16_f32 v148, v208, v209
	v_cvt_pk_bf16_f32 v149, v210, v211
	v_cvt_pk_bf16_f32 v150, v212, v213
	v_cvt_pk_bf16_f32 v151, v214, v215
	global_store_dwordx4 v216, v[148:151], s[10:11] nt
	v_mul_f32_e32 v208, 0xbfb8aa3b, v86
	v_mul_f32_e32 v209, 0xbfb8aa3b, v87
	v_mul_f32_e32 v210, 0xbfb8aa3b, v88
	v_mul_f32_e32 v211, 0xbfb8aa3b, v89
	v_mul_f32_e32 v212, 0xbfb8aa3b, v82
	v_mul_f32_e32 v213, 0xbfb8aa3b, v83
	v_mul_f32_e32 v214, 0xbfb8aa3b, v84
	v_mul_f32_e32 v215, 0xbfb8aa3b, v85
	v_exp_f32_e32 v208, v208
	v_exp_f32_e32 v209, v209
	v_exp_f32_e32 v210, v210
	v_exp_f32_e32 v211, v211
	v_exp_f32_e32 v212, v212
	v_exp_f32_e32 v213, v213
	v_exp_f32_e32 v214, v214
	v_exp_f32_e32 v215, v215
	v_add_f32_e32 v208, 1.0, v208
	v_add_f32_e32 v209, 1.0, v209
	v_add_f32_e32 v210, 1.0, v210
	v_add_f32_e32 v211, 1.0, v211
	v_add_f32_e32 v212, 1.0, v212
	v_add_f32_e32 v213, 1.0, v213
	v_add_f32_e32 v214, 1.0, v214
	v_add_f32_e32 v215, 1.0, v215
	v_rcp_f32_e32 v208, v208
	v_rcp_f32_e32 v209, v209
	v_rcp_f32_e32 v210, v210
	v_rcp_f32_e32 v211, v211
	v_rcp_f32_e32 v212, v212
	v_rcp_f32_e32 v213, v213
	v_rcp_f32_e32 v214, v214
	v_rcp_f32_e32 v215, v215
	v_cvt_pk_bf16_f32 v152, v208, v209
	v_cvt_pk_bf16_f32 v153, v210, v211
	v_cvt_pk_bf16_f32 v154, v212, v213
	v_cvt_pk_bf16_f32 v155, v214, v215
	global_store_dwordx4 v216, v[152:155], s[10:11] offset:256 nt
	s_add_u32 s10, s22, 0x90000
	s_addc_u32 s11, s23, 0
	v_mul_f32_e32 v208, 0xbfb8aa3b, v78
	v_mul_f32_e32 v209, 0xbfb8aa3b, v79
	v_mul_f32_e32 v210, 0xbfb8aa3b, v80
	v_mul_f32_e32 v211, 0xbfb8aa3b, v81
	v_mul_f32_e32 v212, 0xbfb8aa3b, v74
	v_mul_f32_e32 v213, 0xbfb8aa3b, v75
	v_mul_f32_e32 v214, 0xbfb8aa3b, v76
	v_mul_f32_e32 v215, 0xbfb8aa3b, v77
	v_exp_f32_e32 v208, v208
	v_exp_f32_e32 v209, v209
	v_exp_f32_e32 v210, v210
	v_exp_f32_e32 v211, v211
	v_exp_f32_e32 v212, v212
	v_exp_f32_e32 v213, v213
	v_exp_f32_e32 v214, v214
	v_exp_f32_e32 v215, v215
	v_add_f32_e32 v208, 1.0, v208
	v_add_f32_e32 v209, 1.0, v209
	v_add_f32_e32 v210, 1.0, v210
	v_add_f32_e32 v211, 1.0, v211
	v_add_f32_e32 v212, 1.0, v212
	v_add_f32_e32 v213, 1.0, v213
	v_add_f32_e32 v214, 1.0, v214
	v_add_f32_e32 v215, 1.0, v215
	v_rcp_f32_e32 v208, v208
	v_rcp_f32_e32 v209, v209
	v_rcp_f32_e32 v210, v210
	v_rcp_f32_e32 v211, v211
	v_rcp_f32_e32 v212, v212
	v_rcp_f32_e32 v213, v213
	v_rcp_f32_e32 v214, v214
	v_rcp_f32_e32 v215, v215
	v_cvt_pk_bf16_f32 v156, v208, v209
	v_cvt_pk_bf16_f32 v157, v210, v211
	v_cvt_pk_bf16_f32 v158, v212, v213
	v_cvt_pk_bf16_f32 v159, v214, v215
	global_store_dwordx4 v216, v[156:159], s[10:11] nt
	v_mul_f32_e32 v208, 0xbfb8aa3b, v70
	v_mul_f32_e32 v209, 0xbfb8aa3b, v71
	v_mul_f32_e32 v210, 0xbfb8aa3b, v72
	v_mul_f32_e32 v211, 0xbfb8aa3b, v73
	v_mul_f32_e32 v212, 0xbfb8aa3b, v66
	v_mul_f32_e32 v213, 0xbfb8aa3b, v67
	v_mul_f32_e32 v214, 0xbfb8aa3b, v68
	v_mul_f32_e32 v215, 0xbfb8aa3b, v69
	v_exp_f32_e32 v208, v208
	v_exp_f32_e32 v209, v209
	v_exp_f32_e32 v210, v210
	v_exp_f32_e32 v211, v211
	v_exp_f32_e32 v212, v212
	v_exp_f32_e32 v213, v213
	v_exp_f32_e32 v214, v214
	v_exp_f32_e32 v215, v215
	v_add_f32_e32 v208, 1.0, v208
	v_add_f32_e32 v209, 1.0, v209
	v_add_f32_e32 v210, 1.0, v210
	v_add_f32_e32 v211, 1.0, v211
	v_add_f32_e32 v212, 1.0, v212
	v_add_f32_e32 v213, 1.0, v213
	v_add_f32_e32 v214, 1.0, v214
	v_add_f32_e32 v215, 1.0, v215
	v_rcp_f32_e32 v208, v208
	v_rcp_f32_e32 v209, v209
	v_rcp_f32_e32 v210, v210
	v_rcp_f32_e32 v211, v211
	v_rcp_f32_e32 v212, v212
	v_rcp_f32_e32 v213, v213
	v_rcp_f32_e32 v214, v214
	v_rcp_f32_e32 v215, v215
	v_cvt_pk_bf16_f32 v160, v208, v209
	v_cvt_pk_bf16_f32 v161, v210, v211
	v_cvt_pk_bf16_f32 v162, v212, v213
	v_cvt_pk_bf16_f32 v163, v214, v215
	global_store_dwordx4 v216, v[160:163], s[10:11] offset:256 nt
	s_add_u32 s10, s22, 0x180000
	s_addc_u32 s11, s23, 0
	v_mul_f32_e32 v208, 0xbfb8aa3b, v62
	v_mul_f32_e32 v209, 0xbfb8aa3b, v63
	v_mul_f32_e32 v210, 0xbfb8aa3b, v64
	v_mul_f32_e32 v211, 0xbfb8aa3b, v65
	v_mul_f32_e32 v212, 0xbfb8aa3b, v58
	v_mul_f32_e32 v213, 0xbfb8aa3b, v59
	v_mul_f32_e32 v214, 0xbfb8aa3b, v60
	v_mul_f32_e32 v215, 0xbfb8aa3b, v61
	v_exp_f32_e32 v208, v208
	v_exp_f32_e32 v209, v209
	v_exp_f32_e32 v210, v210
	v_exp_f32_e32 v211, v211
	v_exp_f32_e32 v212, v212
	v_exp_f32_e32 v213, v213
	v_exp_f32_e32 v214, v214
	v_exp_f32_e32 v215, v215
	v_add_f32_e32 v208, 1.0, v208
	v_add_f32_e32 v209, 1.0, v209
	v_add_f32_e32 v210, 1.0, v210
	v_add_f32_e32 v211, 1.0, v211
	v_add_f32_e32 v212, 1.0, v212
	v_add_f32_e32 v213, 1.0, v213
	v_add_f32_e32 v214, 1.0, v214
	v_add_f32_e32 v215, 1.0, v215
	v_rcp_f32_e32 v208, v208
	v_rcp_f32_e32 v209, v209
	v_rcp_f32_e32 v210, v210
	v_rcp_f32_e32 v211, v211
	v_rcp_f32_e32 v212, v212
	v_rcp_f32_e32 v213, v213
	v_rcp_f32_e32 v214, v214
	v_rcp_f32_e32 v215, v215
	v_cvt_pk_bf16_f32 v148, v208, v209
	v_cvt_pk_bf16_f32 v149, v210, v211
	v_cvt_pk_bf16_f32 v150, v212, v213
	v_cvt_pk_bf16_f32 v151, v214, v215
	global_store_dwordx4 v216, v[148:151], s[10:11] nt
	v_mul_f32_e32 v208, 0xbfb8aa3b, v54
	v_mul_f32_e32 v209, 0xbfb8aa3b, v55
	v_mul_f32_e32 v210, 0xbfb8aa3b, v56
	v_mul_f32_e32 v211, 0xbfb8aa3b, v57
	v_mul_f32_e32 v212, 0xbfb8aa3b, v50
	v_mul_f32_e32 v213, 0xbfb8aa3b, v51
	v_mul_f32_e32 v214, 0xbfb8aa3b, v52
	v_mul_f32_e32 v215, 0xbfb8aa3b, v53
	v_exp_f32_e32 v208, v208
	v_exp_f32_e32 v209, v209
	v_exp_f32_e32 v210, v210
	v_exp_f32_e32 v211, v211
	v_exp_f32_e32 v212, v212
	v_exp_f32_e32 v213, v213
	v_exp_f32_e32 v214, v214
	v_exp_f32_e32 v215, v215
	v_add_f32_e32 v208, 1.0, v208
	v_add_f32_e32 v209, 1.0, v209
	v_add_f32_e32 v210, 1.0, v210
	v_add_f32_e32 v211, 1.0, v211
	v_add_f32_e32 v212, 1.0, v212
	v_add_f32_e32 v213, 1.0, v213
	v_add_f32_e32 v214, 1.0, v214
	v_add_f32_e32 v215, 1.0, v215
	v_rcp_f32_e32 v208, v208
	v_rcp_f32_e32 v209, v209
	v_rcp_f32_e32 v210, v210
	v_rcp_f32_e32 v211, v211
	v_rcp_f32_e32 v212, v212
	v_rcp_f32_e32 v213, v213
	v_rcp_f32_e32 v214, v214
	v_rcp_f32_e32 v215, v215
	v_cvt_pk_bf16_f32 v152, v208, v209
	v_cvt_pk_bf16_f32 v153, v210, v211
	v_cvt_pk_bf16_f32 v154, v212, v213
	v_cvt_pk_bf16_f32 v155, v214, v215
	global_store_dwordx4 v216, v[152:155], s[10:11] offset:256 nt
	s_add_u32 s10, s22, 0x1b0000
	s_addc_u32 s11, s23, 0
	v_mul_f32_e32 v208, 0xbfb8aa3b, v46
	v_mul_f32_e32 v209, 0xbfb8aa3b, v47
	v_mul_f32_e32 v210, 0xbfb8aa3b, v48
	v_mul_f32_e32 v211, 0xbfb8aa3b, v49
	v_mul_f32_e32 v212, 0xbfb8aa3b, v42
	v_mul_f32_e32 v213, 0xbfb8aa3b, v43
	v_mul_f32_e32 v214, 0xbfb8aa3b, v44
	v_mul_f32_e32 v215, 0xbfb8aa3b, v45
	v_exp_f32_e32 v208, v208
	v_exp_f32_e32 v209, v209
	v_exp_f32_e32 v210, v210
	v_exp_f32_e32 v211, v211
	v_exp_f32_e32 v212, v212
	v_exp_f32_e32 v213, v213
	v_exp_f32_e32 v214, v214
	v_exp_f32_e32 v215, v215
	v_add_f32_e32 v208, 1.0, v208
	v_add_f32_e32 v209, 1.0, v209
	v_add_f32_e32 v210, 1.0, v210
	v_add_f32_e32 v211, 1.0, v211
	v_add_f32_e32 v212, 1.0, v212
	v_add_f32_e32 v213, 1.0, v213
	v_add_f32_e32 v214, 1.0, v214
	v_add_f32_e32 v215, 1.0, v215
	v_rcp_f32_e32 v208, v208
	v_rcp_f32_e32 v209, v209
	v_rcp_f32_e32 v210, v210
	v_rcp_f32_e32 v211, v211
	v_rcp_f32_e32 v212, v212
	v_rcp_f32_e32 v213, v213
	v_rcp_f32_e32 v214, v214
	v_rcp_f32_e32 v215, v215
	v_cvt_pk_bf16_f32 v156, v208, v209
	v_cvt_pk_bf16_f32 v157, v210, v211
	v_cvt_pk_bf16_f32 v158, v212, v213
	v_cvt_pk_bf16_f32 v159, v214, v215
	global_store_dwordx4 v216, v[156:159], s[10:11] nt
	v_mul_f32_e32 v208, 0xbfb8aa3b, v38
	v_mul_f32_e32 v209, 0xbfb8aa3b, v39
	v_mul_f32_e32 v210, 0xbfb8aa3b, v40
	v_mul_f32_e32 v211, 0xbfb8aa3b, v41
	v_mul_f32_e32 v212, 0xbfb8aa3b, v34
	v_mul_f32_e32 v213, 0xbfb8aa3b, v35
	v_mul_f32_e32 v214, 0xbfb8aa3b, v36
	v_mul_f32_e32 v215, 0xbfb8aa3b, v37
	v_exp_f32_e32 v208, v208
	v_exp_f32_e32 v209, v209
	v_exp_f32_e32 v210, v210
	v_exp_f32_e32 v211, v211
	v_exp_f32_e32 v212, v212
	v_exp_f32_e32 v213, v213
	v_exp_f32_e32 v214, v214
	v_exp_f32_e32 v215, v215
	v_add_f32_e32 v208, 1.0, v208
	v_add_f32_e32 v209, 1.0, v209
	v_add_f32_e32 v210, 1.0, v210
	v_add_f32_e32 v211, 1.0, v211
	v_add_f32_e32 v212, 1.0, v212
	v_add_f32_e32 v213, 1.0, v213
	v_add_f32_e32 v214, 1.0, v214
	v_add_f32_e32 v215, 1.0, v215
	v_rcp_f32_e32 v208, v208
	v_rcp_f32_e32 v209, v209
	v_rcp_f32_e32 v210, v210
	v_rcp_f32_e32 v211, v211
	v_rcp_f32_e32 v212, v212
	v_rcp_f32_e32 v213, v213
	v_rcp_f32_e32 v214, v214
	v_rcp_f32_e32 v215, v215
	v_cvt_pk_bf16_f32 v160, v208, v209
	v_cvt_pk_bf16_f32 v161, v210, v211
	v_cvt_pk_bf16_f32 v162, v212, v213
	v_cvt_pk_bf16_f32 v163, v214, v215
	global_store_dwordx4 v216, v[160:163], s[10:11] offset:256 nt
	s_add_u32 s10, s22, 0x1e0000
	s_addc_u32 s11, s23, 0
	v_mul_f32_e32 v208, 0xbfb8aa3b, v28
	v_mul_f32_e32 v209, 0xbfb8aa3b, v29
	v_mul_f32_e32 v210, 0xbfb8aa3b, v30
	v_mul_f32_e32 v211, 0xbfb8aa3b, v31
	v_mul_f32_e32 v212, 0xbfb8aa3b, v24
	v_mul_f32_e32 v213, 0xbfb8aa3b, v25
	v_mul_f32_e32 v214, 0xbfb8aa3b, v26
	v_mul_f32_e32 v215, 0xbfb8aa3b, v27
	v_exp_f32_e32 v208, v208
	v_exp_f32_e32 v209, v209
	v_exp_f32_e32 v210, v210
	v_exp_f32_e32 v211, v211
	v_exp_f32_e32 v212, v212
	v_exp_f32_e32 v213, v213
	v_exp_f32_e32 v214, v214
	v_exp_f32_e32 v215, v215
	v_add_f32_e32 v208, 1.0, v208
	v_add_f32_e32 v209, 1.0, v209
	v_add_f32_e32 v210, 1.0, v210
	v_add_f32_e32 v211, 1.0, v211
	v_add_f32_e32 v212, 1.0, v212
	v_add_f32_e32 v213, 1.0, v213
	v_add_f32_e32 v214, 1.0, v214
	v_add_f32_e32 v215, 1.0, v215
	v_rcp_f32_e32 v208, v208
	v_rcp_f32_e32 v209, v209
	v_rcp_f32_e32 v210, v210
	v_rcp_f32_e32 v211, v211
	v_rcp_f32_e32 v212, v212
	v_rcp_f32_e32 v213, v213
	v_rcp_f32_e32 v214, v214
	v_rcp_f32_e32 v215, v215
	v_cvt_pk_bf16_f32 v148, v208, v209
	v_cvt_pk_bf16_f32 v149, v210, v211
	v_cvt_pk_bf16_f32 v150, v212, v213
	v_cvt_pk_bf16_f32 v151, v214, v215
	global_store_dwordx4 v216, v[148:151], s[10:11] nt
	v_mul_f32_e32 v208, 0xbfb8aa3b, v20
	v_mul_f32_e32 v209, 0xbfb8aa3b, v21
	v_mul_f32_e32 v210, 0xbfb8aa3b, v22
	v_mul_f32_e32 v211, 0xbfb8aa3b, v23
	v_mul_f32_e32 v212, 0xbfb8aa3b, v16
	v_mul_f32_e32 v213, 0xbfb8aa3b, v17
	v_mul_f32_e32 v214, 0xbfb8aa3b, v18
	v_mul_f32_e32 v215, 0xbfb8aa3b, v19
	v_exp_f32_e32 v208, v208
	v_exp_f32_e32 v209, v209
	v_exp_f32_e32 v210, v210
	v_exp_f32_e32 v211, v211
	v_exp_f32_e32 v212, v212
	v_exp_f32_e32 v213, v213
	v_exp_f32_e32 v214, v214
	v_exp_f32_e32 v215, v215
	v_add_f32_e32 v208, 1.0, v208
	v_add_f32_e32 v209, 1.0, v209
	v_add_f32_e32 v210, 1.0, v210
	v_add_f32_e32 v211, 1.0, v211
	v_add_f32_e32 v212, 1.0, v212
	v_add_f32_e32 v213, 1.0, v213
	v_add_f32_e32 v214, 1.0, v214
	v_add_f32_e32 v215, 1.0, v215
	v_rcp_f32_e32 v208, v208
	v_rcp_f32_e32 v209, v209
	v_rcp_f32_e32 v210, v210
	v_rcp_f32_e32 v211, v211
	v_rcp_f32_e32 v212, v212
	v_rcp_f32_e32 v213, v213
	v_rcp_f32_e32 v214, v214
	v_rcp_f32_e32 v215, v215
	v_cvt_pk_bf16_f32 v152, v208, v209
	v_cvt_pk_bf16_f32 v153, v210, v211
	v_cvt_pk_bf16_f32 v154, v212, v213
	v_cvt_pk_bf16_f32 v155, v214, v215
	global_store_dwordx4 v216, v[152:155], s[10:11] offset:256 nt
	s_add_u32 s10, s22, 0x210000
	s_addc_u32 s11, s23, 0
	v_mul_f32_e32 v208, 0xbfb8aa3b, v12
	v_mul_f32_e32 v209, 0xbfb8aa3b, v13
	v_mul_f32_e32 v210, 0xbfb8aa3b, v14
	v_mul_f32_e32 v211, 0xbfb8aa3b, v15
	v_mul_f32_e32 v212, 0xbfb8aa3b, v8
	v_mul_f32_e32 v213, 0xbfb8aa3b, v9
	v_mul_f32_e32 v214, 0xbfb8aa3b, v10
	v_mul_f32_e32 v215, 0xbfb8aa3b, v11
	v_exp_f32_e32 v208, v208
	v_exp_f32_e32 v209, v209
	v_exp_f32_e32 v210, v210
	v_exp_f32_e32 v211, v211
	v_exp_f32_e32 v212, v212
	v_exp_f32_e32 v213, v213
	v_exp_f32_e32 v214, v214
	v_exp_f32_e32 v215, v215
	v_add_f32_e32 v208, 1.0, v208
	v_add_f32_e32 v209, 1.0, v209
	v_add_f32_e32 v210, 1.0, v210
	v_add_f32_e32 v211, 1.0, v211
	v_add_f32_e32 v212, 1.0, v212
	v_add_f32_e32 v213, 1.0, v213
	v_add_f32_e32 v214, 1.0, v214
	v_add_f32_e32 v215, 1.0, v215
	v_rcp_f32_e32 v208, v208
	v_rcp_f32_e32 v209, v209
	v_rcp_f32_e32 v210, v210
	v_rcp_f32_e32 v211, v211
	v_rcp_f32_e32 v212, v212
	v_rcp_f32_e32 v213, v213
	v_rcp_f32_e32 v214, v214
	v_rcp_f32_e32 v215, v215
	v_cvt_pk_bf16_f32 v156, v208, v209
	v_cvt_pk_bf16_f32 v157, v210, v211
	v_cvt_pk_bf16_f32 v158, v212, v213
	v_cvt_pk_bf16_f32 v159, v214, v215
	global_store_dwordx4 v216, v[156:159], s[10:11] nt
	v_mul_f32_e32 v208, 0xbfb8aa3b, v4
	v_mul_f32_e32 v209, 0xbfb8aa3b, v5
	v_mul_f32_e32 v210, 0xbfb8aa3b, v6
	v_mul_f32_e32 v211, 0xbfb8aa3b, v7
	v_mul_f32_e32 v212, 0xbfb8aa3b, v0
	v_mul_f32_e32 v213, 0xbfb8aa3b, v1
	v_mul_f32_e32 v214, 0xbfb8aa3b, v2
	v_mul_f32_e32 v215, 0xbfb8aa3b, v3
	v_exp_f32_e32 v208, v208
	v_exp_f32_e32 v209, v209
	v_exp_f32_e32 v210, v210
	v_exp_f32_e32 v211, v211
	v_exp_f32_e32 v212, v212
	v_exp_f32_e32 v213, v213
	v_exp_f32_e32 v214, v214
	v_exp_f32_e32 v215, v215
	v_add_f32_e32 v208, 1.0, v208
	v_add_f32_e32 v209, 1.0, v209
	v_add_f32_e32 v210, 1.0, v210
	v_add_f32_e32 v211, 1.0, v211
	v_add_f32_e32 v212, 1.0, v212
	v_add_f32_e32 v213, 1.0, v213
	v_add_f32_e32 v214, 1.0, v214
	v_add_f32_e32 v215, 1.0, v215
	v_rcp_f32_e32 v208, v208
	v_rcp_f32_e32 v209, v209
	v_rcp_f32_e32 v210, v210
	v_rcp_f32_e32 v211, v211
	v_rcp_f32_e32 v212, v212
	v_rcp_f32_e32 v213, v213
	v_rcp_f32_e32 v214, v214
	v_rcp_f32_e32 v215, v215
	v_cvt_pk_bf16_f32 v160, v208, v209
	v_cvt_pk_bf16_f32 v161, v210, v211
	v_cvt_pk_bf16_f32 v162, v212, v213
	v_cvt_pk_bf16_f32 v163, v214, v215
	global_store_dwordx4 v216, v[160:163], s[10:11] offset:256 nt
	s_branch .LBB0_364
.Lmain_old:
	s_mov_b64 s[6:7], 0
	s_add_u32 s52, s76, s6
	s_addc_u32 s53, s77, s7
	s_cmp_gt_i32 s51, 7
	s_mov_b64 s[8:9], -1
	s_cbranch_scc0 .LBB0_401
	s_cmp_gt_u32 s51, 15
	s_mov_b64 s[10:11], -1
	s_cbranch_scc0 .LBB0_399
	s_cmp_gt_u32 s51, 23
	s_cbranch_scc0 .LBB0_396
	s_cmp_gt_u32 s51, 31
	s_cbranch_scc0 .LBB0_394
	s_cmp_gt_u32 s51, 43
	s_cbranch_scc0 .LBB0_391
	s_lshl_b32 s10, s51, 8
	s_cmp_gt_u32 s51, 51
	s_cbranch_scc0 .LBB0_388
	s_cmp_gt_u32 s51, 59
	s_cbranch_scc0 .LBB0_385
	s_mov_b64 s[6:7], -1
	s_cmpk_gt_u32 s51, 0x43
	s_cbranch_scc0 .LBB0_382
	s_add_u32 s22, s52, 0x37f51000
	s_addc_u32 s23, s53, 0
	s_add_i32 s30, s10, 0xffffbc00
	s_mov_b64 s[8:9], 0
